# speedup vs baseline: 1.0619x; 1.0038x over previous
.LBB0_376:
	s_or_b64 exec, exec, s[0:1]
	v_lshl_add_u64 v[2:3], v[2:3], 0, v[4:5]
	s_add_i32 s49, s49, 1
	global_store_dword v[2:3], v6, off sc0 sc1

.LBB0_380:
	s_mov_b64 s[0:1], 0
	v_lshl_add_u32 v192, s12, 3, v83
	s_add_u32 s38, s86, s0
	s_addc_u32 s39, s87, s1
	v_and_b32_e32 v193, 63, v192
	v_mov_b32_e32 v87, v85
	v_lshl_add_u64 v[2:3], s[38:39], 0, v[86:87]
	v_lshl_or_b32 v4, v193, 13, v190
	v_mov_b32_e32 v5, v85
	v_lshl_add_u64 v[2:3], v[2:3], 0, v[4:5]
	v_lshl_or_b32 v6, v193, 8, v84
	v_mov_b32_e32 v7, v85
	v_add_co_u32_e32 v4, vcc, s46, v2
	v_lshl_add_u64 v[6:7], s[38:39], 0, v[6:7]
	s_mov_b64 s[12:13], vcc
	v_add_co_u32_e32 v8, vcc, s47, v6
	v_ashrrev_i32_e32 v12, 10, v192
	s_nop 0
	v_addc_co_u32_e32 v9, vcc, 0, v7, vcc
	v_add_co_u32_e32 v10, vcc, s48, v6
	global_load_dwordx2 v[92:93], v[8:9], off offset:192
	global_load_dwordx2 v[94:95], v[8:9], off offset:160
	v_addc_co_u32_e32 v11, vcc, 0, v7, vcc
	global_load_dwordx2 v[96:97], v[8:9], off offset:128
	global_load_dwordx2 v[98:99], v[8:9], off offset:224
	global_load_dwordx2 v[100:101], v[10:11], off offset:224
	global_load_dwordx2 v[102:103], v[10:11], off offset:192
	global_load_dwordx2 v[104:105], v[10:11], off offset:160
	global_load_dwordx2 v[106:107], v[10:11], off offset:128
	global_load_dwordx2 v[108:109], v[8:9], off offset:96
	global_load_dwordx2 v[110:111], v[10:11], off offset:96
	global_load_dwordx2 v[112:113], v[8:9], off offset:64
	global_load_dwordx2 v[114:115], v[10:11], off offset:64
	global_load_dwordx2 v[116:117], v[8:9], off offset:32
	global_load_dwordx2 v[118:119], v[10:11], off offset:32
	global_load_dwordx2 v[120:121], v[8:9], off
	global_load_dwordx2 v[122:123], v[10:11], off
	v_lshl_add_u64 v[8:9], v[2:3], 0, s[18:19]
	v_addc_co_u32_e64 v5, vcc, 0, v3, s[12:13]
	s_waitcnt lgkmcnt(0)
	global_load_dwordx4 v[22:25], v[8:9], off offset:3072
	global_load_dwordx4 v[26:29], v[8:9], off offset:1024
	global_load_dwordx4 v[30:33], v[8:9], off offset:2048
	global_load_dwordx4 v[34:37], v[4:5], off offset:-4096
	global_load_dwordx4 v[38:41], v[4:5], off
	global_load_dwordx4 v[42:45], v[4:5], off offset:1024
	global_load_dwordx4 v[46:49], v[4:5], off offset:2048
	global_load_dwordx4 v[50:53], v[4:5], off offset:3072
	v_ashrrev_i32_e32 v13, 31, v12
	v_mov_b32_e32 v11, v85
	v_lshlrev_b32_e32 v10, 14, v193
	v_lshlrev_b64 v[12:13], 13, v[12:13]
	v_lshl_add_u64 v[10:11], v[12:13], 0, v[10:11]
	v_bfe_u32 v87, v192, 6, 4
	v_or_b32_e32 v2, v10, v82
	v_lshl_or_b32 v10, v87, 9, v2
	v_lshlrev_b64 v[2:3], 5, v[10:11]
	v_mov_b32_e32 v89, v85
	v_lshl_add_u64 v[2:3], s[38:39], 0, v[2:3]
	v_lshl_add_u64 v[2:3], v[2:3], 0, v[88:89]
	v_lshl_add_u64 v[124:125], v[2:3], 0, s[22:23]
	v_lshl_add_u64 v[158:159], v[2:3], 0, s[24:25]
	v_lshl_add_u64 v[160:161], v[2:3], 0, s[26:27]
	v_lshl_add_u64 v[66:67], v[2:3], 0, s[28:29]
	v_mov_b32_e32 v2, 0
	v_lshl_add_u64 v[90:91], v[6:7], 0, s[20:21]
	s_mov_b32 s1, -4
	v_mov_b64_e32 v[162:163], v[124:125]
	v_mov_b32_e32 v3, v2
	v_mov_b32_e32 v4, v2
	v_mov_b32_e32 v5, v2
	v_mov_b32_e32 v6, v2
	v_mov_b32_e32 v7, v2
	v_mov_b32_e32 v8, v2
	v_mov_b32_e32 v9, v2
	v_mov_b32_e32 v10, v2
	v_mov_b32_e32 v11, v2
	v_mov_b32_e32 v12, v2
	v_mov_b32_e32 v13, v2
	v_mov_b32_e32 v14, v2
	v_mov_b32_e32 v15, v2
	v_mov_b32_e32 v16, v2
	v_mov_b32_e32 v17, v2
	v_mov_b32_e32 v18, v2
	v_mov_b32_e32 v19, v2
	v_mov_b32_e32 v20, v2
	v_mov_b32_e32 v21, v2
	v_mov_b32_e32 v54, v2
	v_mov_b32_e32 v55, v2
	v_mov_b32_e32 v56, v2
	v_mov_b32_e32 v57, v2
	v_mov_b32_e32 v58, v2
	v_mov_b32_e32 v59, v2
	v_mov_b32_e32 v60, v2
	v_mov_b32_e32 v61, v2
	v_mov_b32_e32 v62, v2
	v_mov_b32_e32 v63, v2
	v_mov_b32_e32 v64, v2
	v_mov_b32_e32 v65, v2
	s_waitcnt vmcnt(0)
	v_mov_b32_e32 v134, v100
	v_mov_b32_e32 v135, v100
	v_mov_b32_e32 v100, v101
	v_mov_b32_e32 v136, v102
	v_mov_b32_e32 v137, v102
	v_mov_b32_e32 v102, v103
	v_mov_b32_e32 v126, v92
	v_mov_b32_e32 v127, v92
	v_mov_b32_e32 v92, v93
	v_mov_b32_e32 v128, v94
	v_mov_b32_e32 v129, v94
	v_mov_b32_e32 v94, v95
	v_mov_b32_e32 v130, v96
	v_mov_b32_e32 v132, v98
	v_mov_b32_e32 v133, v98
	v_mov_b32_e32 v98, v99
	v_mov_b32_e32 v138, v104
	v_mov_b32_e32 v139, v104
	v_mov_b32_e32 v104, v105
	v_mov_b32_e32 v131, v96
	v_mov_b32_e32 v140, v106
	v_mov_b32_e32 v141, v106
	v_mov_b32_e32 v96, v97
	v_mov_b32_e32 v106, v107
	v_mov_b32_e32 v142, v108
	v_mov_b32_e32 v143, v108
	v_mov_b32_e32 v144, v110
	v_mov_b32_e32 v145, v110
	v_mov_b32_e32 v108, v109
	v_mov_b32_e32 v110, v111
	v_mov_b32_e32 v146, v112
	v_mov_b32_e32 v147, v112
	v_mov_b32_e32 v148, v114
	v_mov_b32_e32 v149, v114
	v_mov_b32_e32 v112, v113
	v_mov_b32_e32 v114, v115
	v_mov_b32_e32 v150, v116
	v_mov_b32_e32 v151, v116
	v_mov_b32_e32 v152, v118
	v_mov_b32_e32 v153, v118
	v_mov_b32_e32 v116, v117
	v_mov_b32_e32 v118, v119
	v_mov_b32_e32 v154, v120
	v_mov_b32_e32 v155, v120
	v_mov_b32_e32 v156, v122
	v_mov_b32_e32 v157, v122
	v_mov_b32_e32 v120, v121
	v_mov_b32_e32 v122, v123
	global_load_dwordx4 v[208:211], v[162:163], off
	global_load_dwordx4 v[212:215], v[158:159], off
	global_load_dwordx4 v[216:219], v[160:161], off
	global_load_dwordx4 v[220:223], v[66:67], off
.LBB0_381:
	s_waitcnt vmcnt(0)
	v_mov_b32_e32 v78, v208
	v_mov_b32_e32 v79, v209
	v_mov_b32_e32 v80, v210
	v_mov_b32_e32 v81, v211
	v_mov_b32_e32 v74, v212
	v_mov_b32_e32 v75, v213
	v_mov_b32_e32 v76, v214
	v_mov_b32_e32 v77, v215
	v_mov_b32_e32 v70, v216
	v_mov_b32_e32 v71, v217
	v_mov_b32_e32 v72, v218
	v_mov_b32_e32 v73, v219
	v_mov_b32_e32 v66, v220
	v_mov_b32_e32 v67, v221
	v_mov_b32_e32 v68, v222
	v_mov_b32_e32 v69, v223
	s_add_i32 s0, s1, 4
	s_add_i32 s12, s1, 5
	s_min_u32 s14, s0, 27
	s_add_i32 s13, s1, 6
	s_min_u32 s12, s12, 27
	s_lshl_b32 s14, s14, 9
	s_add_i32 s1, s1, 7
	s_min_u32 s13, s13, 27
	v_lshl_add_u64 v[158:159], v[124:125], 0, s[14:15]
	s_lshl_b32 s14, s12, 9
	s_min_u32 s40, s1, 27
	v_lshl_add_u64 v[162:163], v[158:159], 0, s[30:31]
	v_lshl_add_u64 v[158:159], v[124:125], 0, s[14:15]
	s_lshl_b32 s14, s13, 9
	v_lshl_add_u64 v[160:161], v[124:125], 0, s[14:15]
	s_lshl_b32 s14, s40, 9
	s_mov_b32 s1, s0
	v_lshl_add_u64 v[158:159], v[158:159], 0, s[30:31]
	v_lshl_add_u64 v[160:161], v[160:161], 0, s[30:31]
	v_lshl_add_u64 v[224:225], v[124:125], 0, s[14:15]
	v_lshl_add_u64 v[224:225], v[224:225], 0, s[30:31]
	global_load_dwordx4 v[208:211], v[162:163], off
	global_load_dwordx4 v[212:215], v[158:159], off
	global_load_dwordx4 v[216:219], v[160:161], off
	global_load_dwordx4 v[220:223], v[224:225], off
	s_cmp_lt_u32 s0, 28
	v_pk_mul_f32 v[200:201], v[154:155], v[62:63]
	v_pk_mul_f32 v[202:203], v[120:121], v[64:65]
	v_pk_fma_f32 v[62:63], v[156:157], v[62:63], v[200:201] op_sel:[0,1,0] op_sel_hi:[1,0,1] neg_lo:[1,0,0]
	v_pk_fma_f32 v[64:65], v[122:123], v[64:65], v[202:203] op_sel:[0,1,0] op_sel_hi:[1,0,1] neg_lo:[1,0,0]
	v_pk_mul_f32 v[204:205], v[150:151], v[58:59]
	v_pk_mul_f32 v[206:207], v[116:117], v[60:61]
	v_pk_fma_f32 v[58:59], v[152:153], v[58:59], v[204:205] op_sel:[0,1,0] op_sel_hi:[1,0,1] neg_lo:[1,0,0]
	v_pk_fma_f32 v[60:61], v[118:119], v[60:61], v[206:207] op_sel:[0,1,0] op_sel_hi:[1,0,1] neg_lo:[1,0,0]
	v_mfma_f32_16x16x32_bf16 v[62:65], v[34:37], v[78:81], v[62:65]
	v_pk_mul_f32 v[200:201], v[146:147], v[54:55]
	v_pk_mul_f32 v[202:203], v[112:113], v[56:57]
	v_pk_fma_f32 v[54:55], v[148:149], v[54:55], v[200:201] op_sel:[0,1,0] op_sel_hi:[1,0,1] neg_lo:[1,0,0]
	v_pk_fma_f32 v[56:57], v[114:115], v[56:57], v[202:203] op_sel:[0,1,0] op_sel_hi:[1,0,1] neg_lo:[1,0,0]
	v_mfma_f32_16x16x32_bf16 v[58:61], v[26:29], v[78:81], v[58:61]
	v_pk_mul_f32 v[204:205], v[142:143], v[18:19]
	v_pk_mul_f32 v[206:207], v[108:109], v[20:21]
	v_pk_fma_f32 v[18:19], v[144:145], v[18:19], v[204:205] op_sel:[0,1,0] op_sel_hi:[1,0,1] neg_lo:[1,0,0]
	v_pk_fma_f32 v[20:21], v[110:111], v[20:21], v[206:207] op_sel:[0,1,0] op_sel_hi:[1,0,1] neg_lo:[1,0,0]
	v_mfma_f32_16x16x32_bf16 v[54:57], v[30:33], v[78:81], v[54:57]
	v_pk_mul_f32 v[200:201], v[130:131], v[14:15]
	v_pk_mul_f32 v[202:203], v[96:97], v[16:17]
	v_pk_fma_f32 v[14:15], v[140:141], v[14:15], v[200:201] op_sel:[0,1,0] op_sel_hi:[1,0,1] neg_lo:[1,0,0]
	v_pk_fma_f32 v[16:17], v[106:107], v[16:17], v[202:203] op_sel:[0,1,0] op_sel_hi:[1,0,1] neg_lo:[1,0,0]
	v_mfma_f32_16x16x32_bf16 v[18:21], v[22:25], v[78:81], v[18:21]
	v_pk_mul_f32 v[204:205], v[128:129], v[10:11]
	v_pk_mul_f32 v[206:207], v[94:95], v[12:13]
	v_pk_fma_f32 v[10:11], v[138:139], v[10:11], v[204:205] op_sel:[0,1,0] op_sel_hi:[1,0,1] neg_lo:[1,0,0]
	v_pk_fma_f32 v[12:13], v[104:105], v[12:13], v[206:207] op_sel:[0,1,0] op_sel_hi:[1,0,1] neg_lo:[1,0,0]
	v_mfma_f32_16x16x32_bf16 v[14:17], v[38:41], v[78:81], v[14:17]
	v_pk_mul_f32 v[200:201], v[126:127], v[6:7]
	v_pk_mul_f32 v[202:203], v[92:93], v[8:9]
	v_pk_fma_f32 v[6:7], v[136:137], v[6:7], v[200:201] op_sel:[0,1,0] op_sel_hi:[1,0,1] neg_lo:[1,0,0]
	v_pk_fma_f32 v[8:9], v[102:103], v[8:9], v[202:203] op_sel:[0,1,0] op_sel_hi:[1,0,1] neg_lo:[1,0,0]
	v_mfma_f32_16x16x32_bf16 v[10:13], v[42:45], v[78:81], v[10:13]
	v_pk_mul_f32 v[204:205], v[132:133], v[2:3]
	v_pk_mul_f32 v[206:207], v[98:99], v[4:5]
	v_pk_fma_f32 v[2:3], v[134:135], v[2:3], v[204:205] op_sel:[0,1,0] op_sel_hi:[1,0,1] neg_lo:[1,0,0]
	v_pk_fma_f32 v[4:5], v[100:101], v[4:5], v[206:207] op_sel:[0,1,0] op_sel_hi:[1,0,1] neg_lo:[1,0,0]
	v_mfma_f32_16x16x32_bf16 v[6:9], v[46:49], v[78:81], v[6:9]
	s_nop 1
	v_mfma_f32_16x16x32_bf16 v[2:5], v[50:53], v[78:81], v[2:5]
	v_pk_mul_f32 v[200:201], v[154:155], v[62:63]
	v_pk_mul_f32 v[202:203], v[120:121], v[64:65]
	v_pk_fma_f32 v[62:63], v[156:157], v[62:63], v[200:201] op_sel:[0,1,0] op_sel_hi:[1,0,1] neg_lo:[1,0,0]
	v_pk_fma_f32 v[64:65], v[122:123], v[64:65], v[202:203] op_sel:[0,1,0] op_sel_hi:[1,0,1] neg_lo:[1,0,0]
	v_pk_mul_f32 v[204:205], v[150:151], v[58:59]
	v_pk_mul_f32 v[206:207], v[116:117], v[60:61]
	v_pk_fma_f32 v[58:59], v[152:153], v[58:59], v[204:205] op_sel:[0,1,0] op_sel_hi:[1,0,1] neg_lo:[1,0,0]
	v_pk_fma_f32 v[60:61], v[118:119], v[60:61], v[206:207] op_sel:[0,1,0] op_sel_hi:[1,0,1] neg_lo:[1,0,0]
	v_mfma_f32_16x16x32_bf16 v[62:65], v[34:37], v[74:77], v[62:65]
	v_pk_mul_f32 v[200:201], v[146:147], v[54:55]
	v_pk_mul_f32 v[202:203], v[112:113], v[56:57]
	v_pk_fma_f32 v[54:55], v[148:149], v[54:55], v[200:201] op_sel:[0,1,0] op_sel_hi:[1,0,1] neg_lo:[1,0,0]
	v_pk_fma_f32 v[56:57], v[114:115], v[56:57], v[202:203] op_sel:[0,1,0] op_sel_hi:[1,0,1] neg_lo:[1,0,0]
	v_mfma_f32_16x16x32_bf16 v[58:61], v[26:29], v[74:77], v[58:61]
	v_pk_mul_f32 v[204:205], v[142:143], v[18:19]
	v_pk_mul_f32 v[206:207], v[108:109], v[20:21]
	v_pk_fma_f32 v[18:19], v[144:145], v[18:19], v[204:205] op_sel:[0,1,0] op_sel_hi:[1,0,1] neg_lo:[1,0,0]
	v_pk_fma_f32 v[20:21], v[110:111], v[20:21], v[206:207] op_sel:[0,1,0] op_sel_hi:[1,0,1] neg_lo:[1,0,0]
	v_mfma_f32_16x16x32_bf16 v[54:57], v[30:33], v[74:77], v[54:57]
	v_pk_mul_f32 v[200:201], v[130:131], v[14:15]
	v_pk_mul_f32 v[202:203], v[96:97], v[16:17]
	v_pk_fma_f32 v[14:15], v[140:141], v[14:15], v[200:201] op_sel:[0,1,0] op_sel_hi:[1,0,1] neg_lo:[1,0,0]
	v_pk_fma_f32 v[16:17], v[106:107], v[16:17], v[202:203] op_sel:[0,1,0] op_sel_hi:[1,0,1] neg_lo:[1,0,0]
	v_mfma_f32_16x16x32_bf16 v[18:21], v[22:25], v[74:77], v[18:21]
	v_pk_mul_f32 v[204:205], v[128:129], v[10:11]
	v_pk_mul_f32 v[206:207], v[94:95], v[12:13]
	v_pk_fma_f32 v[10:11], v[138:139], v[10:11], v[204:205] op_sel:[0,1,0] op_sel_hi:[1,0,1] neg_lo:[1,0,0]
	v_pk_fma_f32 v[12:13], v[104:105], v[12:13], v[206:207] op_sel:[0,1,0] op_sel_hi:[1,0,1] neg_lo:[1,0,0]
	v_mfma_f32_16x16x32_bf16 v[14:17], v[38:41], v[74:77], v[14:17]
	v_pk_mul_f32 v[200:201], v[126:127], v[6:7]
	v_pk_mul_f32 v[202:203], v[92:93], v[8:9]
	v_pk_fma_f32 v[6:7], v[136:137], v[6:7], v[200:201] op_sel:[0,1,0] op_sel_hi:[1,0,1] neg_lo:[1,0,0]
	v_pk_fma_f32 v[8:9], v[102:103], v[8:9], v[202:203] op_sel:[0,1,0] op_sel_hi:[1,0,1] neg_lo:[1,0,0]
	v_mfma_f32_16x16x32_bf16 v[10:13], v[42:45], v[74:77], v[10:13]
	v_pk_mul_f32 v[204:205], v[132:133], v[2:3]
	v_pk_mul_f32 v[206:207], v[98:99], v[4:5]
	v_pk_fma_f32 v[2:3], v[134:135], v[2:3], v[204:205] op_sel:[0,1,0] op_sel_hi:[1,0,1] neg_lo:[1,0,0]
	v_pk_fma_f32 v[4:5], v[100:101], v[4:5], v[206:207] op_sel:[0,1,0] op_sel_hi:[1,0,1] neg_lo:[1,0,0]
	v_mfma_f32_16x16x32_bf16 v[6:9], v[46:49], v[74:77], v[6:9]
	s_nop 1
	v_mfma_f32_16x16x32_bf16 v[2:5], v[50:53], v[74:77], v[2:5]
	v_pk_mul_f32 v[200:201], v[154:155], v[62:63]
	v_pk_mul_f32 v[202:203], v[120:121], v[64:65]
	v_pk_fma_f32 v[62:63], v[156:157], v[62:63], v[200:201] op_sel:[0,1,0] op_sel_hi:[1,0,1] neg_lo:[1,0,0]
	v_pk_fma_f32 v[64:65], v[122:123], v[64:65], v[202:203] op_sel:[0,1,0] op_sel_hi:[1,0,1] neg_lo:[1,0,0]
	v_pk_mul_f32 v[204:205], v[150:151], v[58:59]
	v_pk_mul_f32 v[206:207], v[116:117], v[60:61]
	v_pk_fma_f32 v[58:59], v[152:153], v[58:59], v[204:205] op_sel:[0,1,0] op_sel_hi:[1,0,1] neg_lo:[1,0,0]
	v_pk_fma_f32 v[60:61], v[118:119], v[60:61], v[206:207] op_sel:[0,1,0] op_sel_hi:[1,0,1] neg_lo:[1,0,0]
	v_mfma_f32_16x16x32_bf16 v[62:65], v[34:37], v[70:73], v[62:65]
	v_pk_mul_f32 v[200:201], v[146:147], v[54:55]
	v_pk_mul_f32 v[202:203], v[112:113], v[56:57]
	v_pk_fma_f32 v[54:55], v[148:149], v[54:55], v[200:201] op_sel:[0,1,0] op_sel_hi:[1,0,1] neg_lo:[1,0,0]
	v_pk_fma_f32 v[56:57], v[114:115], v[56:57], v[202:203] op_sel:[0,1,0] op_sel_hi:[1,0,1] neg_lo:[1,0,0]
	v_mfma_f32_16x16x32_bf16 v[58:61], v[26:29], v[70:73], v[58:61]
	v_pk_mul_f32 v[204:205], v[142:143], v[18:19]
	v_pk_mul_f32 v[206:207], v[108:109], v[20:21]
	v_pk_fma_f32 v[18:19], v[144:145], v[18:19], v[204:205] op_sel:[0,1,0] op_sel_hi:[1,0,1] neg_lo:[1,0,0]
	v_pk_fma_f32 v[20:21], v[110:111], v[20:21], v[206:207] op_sel:[0,1,0] op_sel_hi:[1,0,1] neg_lo:[1,0,0]
	v_mfma_f32_16x16x32_bf16 v[54:57], v[30:33], v[70:73], v[54:57]
	v_pk_mul_f32 v[200:201], v[130:131], v[14:15]
	v_pk_mul_f32 v[202:203], v[96:97], v[16:17]
	v_pk_fma_f32 v[14:15], v[140:141], v[14:15], v[200:201] op_sel:[0,1,0] op_sel_hi:[1,0,1] neg_lo:[1,0,0]
	v_pk_fma_f32 v[16:17], v[106:107], v[16:17], v[202:203] op_sel:[0,1,0] op_sel_hi:[1,0,1] neg_lo:[1,0,0]
	v_mfma_f32_16x16x32_bf16 v[18:21], v[22:25], v[70:73], v[18:21]
	v_pk_mul_f32 v[204:205], v[128:129], v[10:11]
	v_pk_mul_f32 v[206:207], v[94:95], v[12:13]
	v_pk_fma_f32 v[10:11], v[138:139], v[10:11], v[204:205] op_sel:[0,1,0] op_sel_hi:[1,0,1] neg_lo:[1,0,0]
	v_pk_fma_f32 v[12:13], v[104:105], v[12:13], v[206:207] op_sel:[0,1,0] op_sel_hi:[1,0,1] neg_lo:[1,0,0]
	v_mfma_f32_16x16x32_bf16 v[14:17], v[38:41], v[70:73], v[14:17]
	v_pk_mul_f32 v[200:201], v[126:127], v[6:7]
	v_pk_mul_f32 v[202:203], v[92:93], v[8:9]
	v_pk_fma_f32 v[6:7], v[136:137], v[6:7], v[200:201] op_sel:[0,1,0] op_sel_hi:[1,0,1] neg_lo:[1,0,0]
	v_pk_fma_f32 v[8:9], v[102:103], v[8:9], v[202:203] op_sel:[0,1,0] op_sel_hi:[1,0,1] neg_lo:[1,0,0]
	v_mfma_f32_16x16x32_bf16 v[10:13], v[42:45], v[70:73], v[10:13]
	v_pk_mul_f32 v[204:205], v[132:133], v[2:3]
	v_pk_mul_f32 v[206:207], v[98:99], v[4:5]
	v_pk_fma_f32 v[2:3], v[134:135], v[2:3], v[204:205] op_sel:[0,1,0] op_sel_hi:[1,0,1] neg_lo:[1,0,0]
	v_pk_fma_f32 v[4:5], v[100:101], v[4:5], v[206:207] op_sel:[0,1,0] op_sel_hi:[1,0,1] neg_lo:[1,0,0]
	v_mfma_f32_16x16x32_bf16 v[6:9], v[46:49], v[70:73], v[6:9]
	s_nop 1
	v_mfma_f32_16x16x32_bf16 v[2:5], v[50:53], v[70:73], v[2:5]
	v_pk_mul_f32 v[200:201], v[154:155], v[62:63]
	v_pk_mul_f32 v[202:203], v[120:121], v[64:65]
	v_pk_fma_f32 v[62:63], v[156:157], v[62:63], v[200:201] op_sel:[0,1,0] op_sel_hi:[1,0,1] neg_lo:[1,0,0]
	v_pk_fma_f32 v[64:65], v[122:123], v[64:65], v[202:203] op_sel:[0,1,0] op_sel_hi:[1,0,1] neg_lo:[1,0,0]
	v_pk_mul_f32 v[204:205], v[150:151], v[58:59]
	v_pk_mul_f32 v[206:207], v[116:117], v[60:61]
	v_pk_fma_f32 v[58:59], v[152:153], v[58:59], v[204:205] op_sel:[0,1,0] op_sel_hi:[1,0,1] neg_lo:[1,0,0]
	v_pk_fma_f32 v[60:61], v[118:119], v[60:61], v[206:207] op_sel:[0,1,0] op_sel_hi:[1,0,1] neg_lo:[1,0,0]
	v_mfma_f32_16x16x32_bf16 v[62:65], v[34:37], v[66:69], v[62:65]
	v_pk_mul_f32 v[200:201], v[146:147], v[54:55]
	v_pk_mul_f32 v[202:203], v[112:113], v[56:57]
	v_pk_fma_f32 v[54:55], v[148:149], v[54:55], v[200:201] op_sel:[0,1,0] op_sel_hi:[1,0,1] neg_lo:[1,0,0]
	v_pk_fma_f32 v[56:57], v[114:115], v[56:57], v[202:203] op_sel:[0,1,0] op_sel_hi:[1,0,1] neg_lo:[1,0,0]
	v_mfma_f32_16x16x32_bf16 v[58:61], v[26:29], v[66:69], v[58:61]
	v_pk_mul_f32 v[204:205], v[142:143], v[18:19]
	v_pk_mul_f32 v[206:207], v[108:109], v[20:21]
	v_pk_fma_f32 v[18:19], v[144:145], v[18:19], v[204:205] op_sel:[0,1,0] op_sel_hi:[1,0,1] neg_lo:[1,0,0]
	v_pk_fma_f32 v[20:21], v[110:111], v[20:21], v[206:207] op_sel:[0,1,0] op_sel_hi:[1,0,1] neg_lo:[1,0,0]
	v_mfma_f32_16x16x32_bf16 v[54:57], v[30:33], v[66:69], v[54:57]
	v_pk_mul_f32 v[200:201], v[130:131], v[14:15]
	v_pk_mul_f32 v[202:203], v[96:97], v[16:17]
	v_pk_fma_f32 v[14:15], v[140:141], v[14:15], v[200:201] op_sel:[0,1,0] op_sel_hi:[1,0,1] neg_lo:[1,0,0]
	v_pk_fma_f32 v[16:17], v[106:107], v[16:17], v[202:203] op_sel:[0,1,0] op_sel_hi:[1,0,1] neg_lo:[1,0,0]
	v_mfma_f32_16x16x32_bf16 v[18:21], v[22:25], v[66:69], v[18:21]
	v_pk_mul_f32 v[204:205], v[128:129], v[10:11]
	v_pk_mul_f32 v[206:207], v[94:95], v[12:13]
	v_pk_fma_f32 v[10:11], v[138:139], v[10:11], v[204:205] op_sel:[0,1,0] op_sel_hi:[1,0,1] neg_lo:[1,0,0]
	v_pk_fma_f32 v[12:13], v[104:105], v[12:13], v[206:207] op_sel:[0,1,0] op_sel_hi:[1,0,1] neg_lo:[1,0,0]
	v_mfma_f32_16x16x32_bf16 v[14:17], v[38:41], v[66:69], v[14:17]
	v_pk_mul_f32 v[200:201], v[126:127], v[6:7]
	v_pk_mul_f32 v[202:203], v[92:93], v[8:9]
	v_pk_fma_f32 v[6:7], v[136:137], v[6:7], v[200:201] op_sel:[0,1,0] op_sel_hi:[1,0,1] neg_lo:[1,0,0]
	v_pk_fma_f32 v[8:9], v[102:103], v[8:9], v[202:203] op_sel:[0,1,0] op_sel_hi:[1,0,1] neg_lo:[1,0,0]
	v_mfma_f32_16x16x32_bf16 v[10:13], v[42:45], v[66:69], v[10:13]
	v_pk_mul_f32 v[204:205], v[132:133], v[2:3]
	v_pk_mul_f32 v[206:207], v[98:99], v[4:5]
	v_pk_fma_f32 v[2:3], v[134:135], v[2:3], v[204:205] op_sel:[0,1,0] op_sel_hi:[1,0,1] neg_lo:[1,0,0]
	v_pk_fma_f32 v[4:5], v[100:101], v[4:5], v[206:207] op_sel:[0,1,0] op_sel_hi:[1,0,1] neg_lo:[1,0,0]
	v_mfma_f32_16x16x32_bf16 v[6:9], v[46:49], v[66:69], v[6:9]
	s_nop 1
	v_mfma_f32_16x16x32_bf16 v[2:5], v[50:53], v[66:69], v[2:5]
	s_cbranch_scc1 .LBB0_381
	global_load_dwordx2 v[32:33], v[90:91], off
	v_add_co_u32_e32 v22, vcc, 0x4000, v90
	s_waitcnt vmcnt(0)
	v_add_f32_e32 v38, v32, v32
	v_addc_co_u32_e32 v23, vcc, 0, v91, vcc
	global_load_dwordx2 v[36:37], v[22:23], off
	global_load_dwordx2 v[24:25], v[22:23], off offset:32
	global_load_dwordx2 v[26:27], v[90:91], off offset:32
	global_load_dwordx2 v[34:35], v[90:91], off offset:64
	global_load_dwordx2 v[28:29], v[90:91], off offset:96
	global_load_dwordx2 v[42:43], v[22:23], off offset:64
	global_load_dwordx2 v[30:31], v[22:23], off offset:96
	v_add_f32_e32 v39, v33, v33
	s_waitcnt vmcnt(6)
	v_fmamk_f32 v40, v36, 0x80000000, v32
	v_fma_f32 v41, 0, v32, v36
	v_mul_f32_e32 v44, v36, v36
	v_mul_f32_e32 v36, v38, v36
	v_fmamk_f32 v38, v37, 0x80000000, v33
	v_fma_f32 v45, 0, v33, v37
	v_mul_f32_e32 v46, v37, v37
	v_mul_f32_e32 v37, v39, v37
	v_cndmask_b32_e64 v40, 1.0, v40, s[10:11]
	v_cndmask_b32_e64 v38, 1.0, v38, s[10:11]
	v_cndmask_b32_e64 v41, 0, v41, s[10:11]
	v_fma_f32 v32, v32, v32, -v44
	v_cndmask_b32_e64 v45, 0, v45, s[10:11]
	v_fma_f32 v33, v33, v33, -v46
	v_mul_f32_e32 v50, v36, v40
	v_mul_f32_e32 v53, v37, v38
	v_mul_f32_e32 v44, v36, v36
	v_mul_f32_e32 v46, v37, v37
	v_mul_f32_e32 v49, v36, v41
	v_add_f32_e32 v51, v32, v32
	v_mul_f32_e32 v52, v37, v45
	v_add_f32_e32 v66, v33, v33
	v_fmac_f32_e32 v50, v32, v41
	v_fmac_f32_e32 v53, v33, v45
	v_fma_f32 v44, v32, v32, -v44
	v_fma_f32 v46, v33, v33, -v46
	v_fma_f32 v49, v32, v40, -v49
	v_mul_f32_e32 v32, v36, v51
	v_fma_f32 v51, v33, v38, -v52
	v_mul_f32_e32 v33, v37, v66
	v_cndmask_b32_e64 v41, v41, v50, s[4:5]
	v_cndmask_b32_e64 v45, v45, v53, s[4:5]
	v_add_f32_e32 v36, v44, v44
	v_cndmask_b32_e64 v40, v40, v49, s[4:5]
	v_mul_f32_e32 v49, v32, v32
	v_cndmask_b32_e64 v38, v38, v51, s[4:5]
	v_mul_f32_e32 v51, v32, v41
	v_mul_f32_e32 v52, v44, v41
	v_mul_f32_e32 v53, v33, v45
	v_mul_f32_e32 v66, v46, v45
	v_add_f32_e32 v37, v46, v46
	v_mul_f32_e32 v36, v32, v36
	v_mul_f32_e32 v50, v33, v33
	v_fma_f32 v49, v44, v44, -v49
	v_fma_f32 v44, v44, v40, -v51
	v_fmac_f32_e32 v52, v32, v40
	v_fma_f32 v32, v46, v38, -v53
	v_fmac_f32_e32 v66, v33, v38
	v_mul_f32_e32 v37, v33, v37
	v_fma_f32 v50, v46, v46, -v50
	v_cndmask_b32_e64 v33, v40, v44, s[6:7]
	v_cndmask_b32_e64 v40, v41, v52, s[6:7]
	v_cndmask_b32_e64 v32, v38, v32, s[6:7]
	v_cndmask_b32_e64 v38, v45, v66, s[6:7]
	v_mul_f32_e32 v41, v36, v40
	v_mul_f32_e32 v44, v49, v40
	v_mul_f32_e32 v45, v37, v38
	v_mul_f32_e32 v46, v50, v38
	s_waitcnt vmcnt(5)
	v_mul_f32_e32 v48, v24, v24
	v_fma_f32 v41, v49, v33, -v41
	v_fmac_f32_e32 v44, v36, v33
	v_fma_f32 v36, v50, v32, -v45
	v_fmac_f32_e32 v46, v37, v32
	s_waitcnt vmcnt(4)
	v_fmamk_f32 v39, v24, 0x80000000, v26
	v_fma_f32 v47, 0, v26, v24
	v_fma_f32 v48, v26, v26, -v48
	v_cndmask_b32_e64 v41, v33, v41, s[8:9]
	v_cndmask_b32_e64 v33, v40, v44, s[8:9]
	v_cndmask_b32_e64 v40, v32, v36, s[8:9]
	v_cndmask_b32_e64 v36, v38, v46, s[8:9]
	v_add_f32_e32 v26, v26, v26
	v_cndmask_b32_e64 v39, 1.0, v39, s[10:11]
	v_cndmask_b32_e64 v47, 0, v47, s[10:11]
	v_mul_f32_e32 v38, v65, v36
	v_mul_f32_e32 v24, v26, v24
	v_mul_f32_e32 v37, v63, v33
	v_mul_f32_e32 v32, v62, v33
	v_mul_f32_e32 v33, v64, v36
	v_fma_f32 v36, v64, v40, -v38
	v_mul_f32_e32 v26, v24, v47
	v_mul_f32_e32 v38, v24, v39
	v_fmac_f32_e32 v33, v65, v40
	v_fma_f32 v26, v48, v39, -v26
	v_fmac_f32_e32 v38, v48, v47
	v_add_f32_e32 v40, v48, v48
	v_cndmask_b32_e64 v26, v39, v26, s[4:5]
	v_cndmask_b32_e64 v38, v47, v38, s[4:5]
	v_mul_f32_e32 v39, v24, v24
	v_mul_f32_e32 v24, v24, v40
	v_fma_f32 v39, v48, v48, -v39
	v_mul_f32_e32 v40, v24, v38
	v_fma_f32 v37, v62, v41, -v37
	v_fmac_f32_e32 v32, v63, v41
	v_fma_f32 v40, v39, v26, -v40
	v_mul_f32_e32 v41, v39, v38
	v_fmac_f32_e32 v41, v24, v26
	v_cndmask_b32_e64 v26, v26, v40, s[6:7]
	v_mul_f32_e32 v40, v24, v24
	v_fma_f32 v40, v39, v39, -v40
	v_add_f32_e32 v39, v39, v39
	v_cndmask_b32_e64 v38, v38, v41, s[6:7]
	v_mul_f32_e32 v24, v24, v39
	v_mul_f32_e32 v39, v24, v38
	v_fma_f32 v39, v40, v26, -v39
	v_mul_f32_e32 v40, v40, v38
	v_fmac_f32_e32 v40, v24, v26
	v_cndmask_b32_e64 v24, v26, v39, s[8:9]
	v_cndmask_b32_e64 v26, v38, v40, s[8:9]
	v_mul_f32_e32 v38, v59, v26
	v_mul_f32_e32 v39, v58, v26
	v_mul_f32_e32 v40, v25, v25
	v_fma_f32 v38, v58, v24, -v38
	v_fmac_f32_e32 v39, v59, v24
	v_fmamk_f32 v24, v25, 0x80000000, v27
	v_fma_f32 v26, 0, v27, v25
	v_fma_f32 v40, v27, v27, -v40
	v_add_f32_e32 v27, v27, v27
	v_cndmask_b32_e64 v26, 0, v26, s[10:11]
	v_mul_f32_e32 v25, v27, v25
	v_cndmask_b32_e64 v24, 1.0, v24, s[10:11]
	v_mul_f32_e32 v27, v25, v26
	v_fma_f32 v27, v40, v24, -v27
	v_mul_f32_e32 v41, v25, v24
	v_cndmask_b32_e64 v24, v24, v27, s[4:5]
	v_mul_f32_e32 v27, v25, v25
	v_fmac_f32_e32 v41, v40, v26
	v_fma_f32 v27, v40, v40, -v27
	v_add_f32_e32 v40, v40, v40
	v_cndmask_b32_e64 v26, v26, v41, s[4:5]
	v_mul_f32_e32 v25, v25, v40
	v_mul_f32_e32 v40, v25, v26
	v_fma_f32 v40, v27, v24, -v40
	v_mul_f32_e32 v41, v27, v26
	v_fmac_f32_e32 v41, v25, v24
	v_cndmask_b32_e64 v24, v24, v40, s[6:7]
	v_mul_f32_e32 v40, v25, v25
	v_fma_f32 v40, v27, v27, -v40
	v_add_f32_e32 v27, v27, v27
	v_cndmask_b32_e64 v26, v26, v41, s[6:7]
	v_mul_f32_e32 v25, v25, v27
	v_mul_f32_e32 v27, v25, v26
	v_fma_f32 v27, v40, v24, -v27
	v_mul_f32_e32 v40, v40, v26
	v_fmac_f32_e32 v40, v25, v24
	v_cndmask_b32_e64 v25, v26, v40, s[8:9]
	v_cndmask_b32_e64 v24, v24, v27, s[8:9]
	v_mul_f32_e32 v26, v61, v25
	v_mul_f32_e32 v41, v60, v25
	s_waitcnt vmcnt(1)
	v_fma_f32 v25, 0, v34, v42
	v_add_f32_e32 v27, v34, v34
	v_fma_f32 v40, v60, v24, -v26
	v_fmac_f32_e32 v41, v61, v24
	v_fmamk_f32 v24, v42, 0x80000000, v34
	v_cndmask_b32_e64 v25, 0, v25, s[10:11]
	v_mul_f32_e32 v26, v42, v42
	v_mul_f32_e32 v27, v27, v42
	v_cndmask_b32_e64 v24, 1.0, v24, s[10:11]
	v_fma_f32 v26, v34, v34, -v26
	v_mul_f32_e32 v34, v27, v25
	v_fma_f32 v34, v26, v24, -v34
	v_mul_f32_e32 v42, v27, v24
	v_cndmask_b32_e64 v24, v24, v34, s[4:5]
	v_mul_f32_e32 v34, v27, v27
	v_fmac_f32_e32 v42, v26, v25
	v_fma_f32 v34, v26, v26, -v34
	v_add_f32_e32 v26, v26, v26
	v_cndmask_b32_e64 v25, v25, v42, s[4:5]
	v_mul_f32_e32 v26, v27, v26
	v_mul_f32_e32 v27, v26, v25
	v_fma_f32 v27, v34, v24, -v27
	v_mul_f32_e32 v42, v34, v25
	v_fmac_f32_e32 v42, v26, v24
	v_cndmask_b32_e64 v24, v24, v27, s[6:7]
	v_mul_f32_e32 v27, v26, v26
	v_fma_f32 v27, v34, v34, -v27
	v_add_f32_e32 v34, v34, v34
	v_cndmask_b32_e64 v25, v25, v42, s[6:7]
	v_mul_f32_e32 v26, v26, v34
	v_mul_f32_e32 v34, v26, v25
	v_fma_f32 v34, v27, v24, -v34
	v_mul_f32_e32 v27, v27, v25
	v_fmac_f32_e32 v27, v26, v24
	v_cndmask_b32_e64 v25, v25, v27, s[8:9]
	v_cndmask_b32_e64 v24, v24, v34, s[8:9]
	v_mul_f32_e32 v26, v55, v25
	v_mul_f32_e32 v42, v54, v25
	v_fma_f32 v25, 0, v35, v43
	v_add_f32_e32 v27, v35, v35
	v_fma_f32 v34, v54, v24, -v26
	v_fmac_f32_e32 v42, v55, v24
	v_fmamk_f32 v24, v43, 0x80000000, v35
	v_cndmask_b32_e64 v25, 0, v25, s[10:11]
	v_mul_f32_e32 v26, v43, v43
	v_mul_f32_e32 v27, v27, v43
	v_cndmask_b32_e64 v24, 1.0, v24, s[10:11]
	v_fma_f32 v26, v35, v35, -v26
	v_mul_f32_e32 v35, v27, v25
	v_fma_f32 v35, v26, v24, -v35
	v_mul_f32_e32 v43, v27, v24
	v_cndmask_b32_e64 v24, v24, v35, s[4:5]
	v_mul_f32_e32 v35, v27, v27
	v_fmac_f32_e32 v43, v26, v25
	v_fma_f32 v35, v26, v26, -v35
	v_add_f32_e32 v26, v26, v26
	v_cndmask_b32_e64 v25, v25, v43, s[4:5]
	v_mul_f32_e32 v26, v27, v26
	v_mul_f32_e32 v27, v26, v25
	v_fma_f32 v27, v35, v24, -v27
	v_mul_f32_e32 v43, v35, v25
	v_fmac_f32_e32 v43, v26, v24
	v_cndmask_b32_e64 v24, v24, v27, s[6:7]
	v_mul_f32_e32 v27, v26, v26
	v_fma_f32 v27, v35, v35, -v27
	v_add_f32_e32 v35, v35, v35
	v_cndmask_b32_e64 v25, v25, v43, s[6:7]
	v_mul_f32_e32 v26, v26, v35
	v_mul_f32_e32 v35, v26, v25
	v_fma_f32 v35, v27, v24, -v35
	v_mul_f32_e32 v27, v27, v25
	v_fmac_f32_e32 v27, v26, v24
	v_cndmask_b32_e64 v25, v25, v27, s[8:9]
	v_cndmask_b32_e64 v24, v24, v35, s[8:9]
	v_mul_f32_e32 v26, v57, v25
	v_mul_f32_e32 v35, v56, v25
	v_fma_f32 v43, v56, v24, -v26
	v_fmac_f32_e32 v35, v57, v24
	s_waitcnt vmcnt(0)
	v_fmamk_f32 v24, v30, 0x80000000, v28
	v_cndmask_b32_e64 v45, 1.0, v24, s[10:11]
	global_load_dwordx2 v[24:25], v[90:91], off offset:128
	global_load_dwordx2 v[26:27], v[22:23], off offset:128
	v_mul_f32_e32 v46, v30, v30
	v_fma_f32 v44, 0, v28, v30
	v_fma_f32 v46, v28, v28, -v46
	v_add_f32_e32 v28, v28, v28
	v_cndmask_b32_e64 v44, 0, v44, s[10:11]
	v_mul_f32_e32 v28, v28, v30
	v_mul_f32_e32 v30, v28, v44
	v_fma_f32 v30, v46, v45, -v30
	v_mul_f32_e32 v47, v28, v45
	v_cndmask_b32_e64 v30, v45, v30, s[4:5]
	v_mul_f32_e32 v45, v28, v28
	v_fmac_f32_e32 v47, v46, v44
	v_fma_f32 v45, v46, v46, -v45
	v_add_f32_e32 v46, v46, v46
	v_cndmask_b32_e64 v44, v44, v47, s[4:5]
	v_mul_f32_e32 v28, v28, v46
	v_mul_f32_e32 v46, v28, v44
	v_fma_f32 v46, v45, v30, -v46
	v_mul_f32_e32 v47, v45, v44
	v_fmac_f32_e32 v47, v28, v30
	v_cndmask_b32_e64 v30, v30, v46, s[6:7]
	v_mul_f32_e32 v46, v28, v28
	v_fma_f32 v46, v45, v45, -v46
	v_add_f32_e32 v45, v45, v45
	v_cndmask_b32_e64 v44, v44, v47, s[6:7]
	v_mul_f32_e32 v28, v28, v45
	v_mul_f32_e32 v45, v28, v44
	v_fma_f32 v45, v46, v30, -v45
	v_mul_f32_e32 v46, v46, v44
	v_fmac_f32_e32 v46, v28, v30
	v_cndmask_b32_e64 v28, v30, v45, s[8:9]
	v_cndmask_b32_e64 v30, v44, v46, s[8:9]
	v_mul_f32_e32 v44, v19, v30
	v_mul_f32_e32 v45, v18, v30
	v_fma_f32 v44, v18, v28, -v44
	v_fmac_f32_e32 v45, v19, v28
	v_mul_f32_e32 v28, v31, v31
	v_fmamk_f32 v18, v31, 0x80000000, v29
	v_fma_f32 v19, 0, v29, v31
	v_fma_f32 v28, v29, v29, -v28
	v_add_f32_e32 v29, v29, v29
	v_cndmask_b32_e64 v19, 0, v19, s[10:11]
	v_mul_f32_e32 v29, v29, v31
	v_cndmask_b32_e64 v18, 1.0, v18, s[10:11]
	v_mul_f32_e32 v30, v29, v19
	v_fma_f32 v30, v28, v18, -v30
	v_mul_f32_e32 v31, v29, v18
	v_cndmask_b32_e64 v18, v18, v30, s[4:5]
	v_mul_f32_e32 v30, v29, v29
	v_fmac_f32_e32 v31, v28, v19
	v_fma_f32 v30, v28, v28, -v30
	v_add_f32_e32 v28, v28, v28
	v_cndmask_b32_e64 v19, v19, v31, s[4:5]
	v_mul_f32_e32 v28, v29, v28
	v_mul_f32_e32 v29, v28, v19
	v_fma_f32 v29, v30, v18, -v29
	v_mul_f32_e32 v31, v30, v19
	v_fmac_f32_e32 v31, v28, v18
	v_cndmask_b32_e64 v18, v18, v29, s[6:7]
	v_mul_f32_e32 v29, v28, v28
	v_fma_f32 v29, v30, v30, -v29
	v_add_f32_e32 v30, v30, v30
	v_cndmask_b32_e64 v19, v19, v31, s[6:7]
	v_mul_f32_e32 v28, v28, v30
	v_mul_f32_e32 v30, v28, v19
	v_fma_f32 v30, v29, v18, -v30
	v_mul_f32_e32 v29, v29, v19
	v_fmac_f32_e32 v29, v28, v18
	v_cndmask_b32_e64 v19, v19, v29, s[8:9]
	v_cndmask_b32_e64 v18, v18, v30, s[8:9]
	v_mul_f32_e32 v28, v21, v19
	v_mul_f32_e32 v47, v20, v19
	v_fma_f32 v46, v20, v18, -v28
	v_fmac_f32_e32 v47, v21, v18
	global_load_dwordx2 v[18:19], v[22:23], off offset:160
	global_load_dwordx2 v[20:21], v[90:91], off offset:160
	global_load_dwordx2 v[28:29], v[90:91], off offset:192
	global_load_dwordx2 v[30:31], v[90:91], off offset:224
	global_load_dwordx2 v[48:49], v[22:23], off offset:192
	s_nop 0
	global_load_dwordx2 v[22:23], v[22:23], off offset:224
	s_waitcnt vmcnt(6)
	v_mul_f32_e32 v52, v26, v26
	v_fmamk_f32 v50, v26, 0x80000000, v24
	v_fma_f32 v51, 0, v24, v26
	v_fma_f32 v52, v24, v24, -v52
	v_add_f32_e32 v24, v24, v24
	v_cndmask_b32_e64 v50, 1.0, v50, s[10:11]
	v_cndmask_b32_e64 v51, 0, v51, s[10:11]
	v_mul_f32_e32 v24, v24, v26
	v_mul_f32_e32 v26, v24, v51
	v_mul_f32_e32 v53, v24, v50
	v_fma_f32 v26, v52, v50, -v26
	v_fmac_f32_e32 v53, v52, v51
	v_cndmask_b32_e64 v26, v50, v26, s[4:5]
	v_cndmask_b32_e64 v50, v51, v53, s[4:5]
	v_mul_f32_e32 v51, v24, v24
	v_fma_f32 v51, v52, v52, -v51
	v_add_f32_e32 v52, v52, v52
	v_mul_f32_e32 v24, v24, v52
	v_mul_f32_e32 v52, v24, v50
	v_fma_f32 v52, v51, v26, -v52
	v_mul_f32_e32 v53, v51, v50
	v_fmac_f32_e32 v53, v24, v26
	v_cndmask_b32_e64 v26, v26, v52, s[6:7]
	v_mul_f32_e32 v52, v24, v24
	v_fma_f32 v52, v51, v51, -v52
	v_add_f32_e32 v51, v51, v51
	v_cndmask_b32_e64 v50, v50, v53, s[6:7]
	v_mul_f32_e32 v24, v24, v51
	v_mul_f32_e32 v51, v24, v50
	v_fma_f32 v51, v52, v26, -v51
	v_mul_f32_e32 v52, v52, v50
	v_fmac_f32_e32 v52, v24, v26
	v_cndmask_b32_e64 v24, v26, v51, s[8:9]
	v_cndmask_b32_e64 v26, v50, v52, s[8:9]
	v_mul_f32_e32 v50, v15, v26
	v_fma_f32 v50, v14, v24, -v50
	v_mul_f32_e32 v14, v14, v26
	v_mul_f32_e32 v26, v27, v27
	v_fmac_f32_e32 v14, v15, v24
	v_fmamk_f32 v15, v27, 0x80000000, v25
	v_fma_f32 v24, 0, v25, v27
	v_fma_f32 v26, v25, v25, -v26
	v_add_f32_e32 v25, v25, v25
	v_cndmask_b32_e64 v24, 0, v24, s[10:11]
	v_mul_f32_e32 v25, v25, v27
	v_cndmask_b32_e64 v15, 1.0, v15, s[10:11]
	v_mul_f32_e32 v27, v25, v24
	v_fma_f32 v27, v26, v15, -v27
	v_mul_f32_e32 v51, v25, v15
	v_cndmask_b32_e64 v15, v15, v27, s[4:5]
	v_mul_f32_e32 v27, v25, v25
	v_fmac_f32_e32 v51, v26, v24
	v_fma_f32 v27, v26, v26, -v27
	v_add_f32_e32 v26, v26, v26
	v_cndmask_b32_e64 v24, v24, v51, s[4:5]
	v_mul_f32_e32 v25, v25, v26
	v_mul_f32_e32 v26, v25, v24
	v_fma_f32 v26, v27, v15, -v26
	v_mul_f32_e32 v51, v27, v24
	v_fmac_f32_e32 v51, v25, v15
	v_cndmask_b32_e64 v15, v15, v26, s[6:7]
	v_mul_f32_e32 v26, v25, v25
	v_fma_f32 v26, v27, v27, -v26
	v_add_f32_e32 v27, v27, v27
	v_cndmask_b32_e64 v24, v24, v51, s[6:7]
	v_mul_f32_e32 v25, v25, v27
	v_mul_f32_e32 v27, v25, v24
	v_fma_f32 v27, v26, v15, -v27
	v_mul_f32_e32 v26, v26, v24
	v_fmac_f32_e32 v26, v25, v15
	v_cndmask_b32_e64 v24, v24, v26, s[8:9]
	v_cndmask_b32_e64 v15, v15, v27, s[8:9]
	v_mul_f32_e32 v25, v17, v24
	v_fma_f32 v25, v16, v15, -v25
	v_mul_f32_e32 v16, v16, v24
	s_waitcnt vmcnt(5)
	v_mul_f32_e32 v24, v18, v18
	v_fmac_f32_e32 v16, v17, v15
	s_waitcnt vmcnt(4)
	v_fmamk_f32 v15, v18, 0x80000000, v20
	v_fma_f32 v17, 0, v20, v18
	v_fma_f32 v24, v20, v20, -v24
	v_add_f32_e32 v20, v20, v20
	v_cndmask_b32_e64 v17, 0, v17, s[10:11]
	v_mul_f32_e32 v18, v20, v18
	v_cndmask_b32_e64 v15, 1.0, v15, s[10:11]
	v_mul_f32_e32 v20, v18, v17
	v_fma_f32 v20, v24, v15, -v20
	v_mul_f32_e32 v26, v18, v15
	v_cndmask_b32_e64 v15, v15, v20, s[4:5]
	v_mul_f32_e32 v20, v18, v18
	v_fmac_f32_e32 v26, v24, v17
	v_fma_f32 v20, v24, v24, -v20
	v_add_f32_e32 v24, v24, v24
	v_cndmask_b32_e64 v17, v17, v26, s[4:5]
	v_mul_f32_e32 v18, v18, v24
	v_mul_f32_e32 v24, v18, v17
	v_fma_f32 v24, v20, v15, -v24
	v_mul_f32_e32 v26, v20, v17
	v_fmac_f32_e32 v26, v18, v15
	v_cndmask_b32_e64 v15, v15, v24, s[6:7]
	v_mul_f32_e32 v24, v18, v18
	v_fma_f32 v24, v20, v20, -v24
	v_add_f32_e32 v20, v20, v20
	v_cndmask_b32_e64 v17, v17, v26, s[6:7]
	v_mul_f32_e32 v18, v18, v20
	v_mul_f32_e32 v20, v18, v17
	v_fma_f32 v20, v24, v15, -v20
	v_mul_f32_e32 v24, v24, v17
	v_fmac_f32_e32 v24, v18, v15
	v_cndmask_b32_e64 v17, v17, v24, s[8:9]
	v_cndmask_b32_e64 v15, v15, v20, s[8:9]
	v_mul_f32_e32 v18, v11, v17
	v_fma_f32 v18, v10, v15, -v18
	v_mul_f32_e32 v10, v10, v17
	v_fmac_f32_e32 v10, v11, v15
	v_fma_f32 v15, 0, v21, v19
	v_add_f32_e32 v20, v21, v21
	v_fmamk_f32 v11, v19, 0x80000000, v21
	v_cndmask_b32_e64 v15, 0, v15, s[10:11]
	v_mul_f32_e32 v17, v19, v19
	v_mul_f32_e32 v19, v20, v19
	v_cndmask_b32_e64 v11, 1.0, v11, s[10:11]
	v_fma_f32 v17, v21, v21, -v17
	v_mul_f32_e32 v20, v19, v15
	v_fma_f32 v20, v17, v11, -v20
	v_mul_f32_e32 v21, v19, v11
	v_cndmask_b32_e64 v11, v11, v20, s[4:5]
	v_mul_f32_e32 v20, v19, v19
	v_fmac_f32_e32 v21, v17, v15
	v_fma_f32 v20, v17, v17, -v20
	v_add_f32_e32 v17, v17, v17
	v_cndmask_b32_e64 v15, v15, v21, s[4:5]
	v_mul_f32_e32 v17, v19, v17
	v_mul_f32_e32 v19, v17, v15
	v_fma_f32 v19, v20, v11, -v19
	v_mul_f32_e32 v21, v20, v15
	v_fmac_f32_e32 v21, v17, v11
	v_cndmask_b32_e64 v11, v11, v19, s[6:7]
	v_mul_f32_e32 v19, v17, v17
	v_fma_f32 v19, v20, v20, -v19
	v_add_f32_e32 v20, v20, v20
	v_cndmask_b32_e64 v15, v15, v21, s[6:7]
	v_mul_f32_e32 v17, v17, v20
	v_mul_f32_e32 v20, v17, v15
	v_fma_f32 v20, v19, v11, -v20
	v_mul_f32_e32 v19, v19, v15
	v_fmac_f32_e32 v19, v17, v11
	v_cndmask_b32_e64 v15, v15, v19, s[8:9]
	v_cndmask_b32_e64 v11, v11, v20, s[8:9]
	v_mul_f32_e32 v17, v13, v15
	v_fma_f32 v17, v12, v11, -v17
	v_mul_f32_e32 v12, v12, v15
	v_fmac_f32_e32 v12, v13, v11
	s_waitcnt vmcnt(1)
	v_fma_f32 v13, 0, v28, v48
	v_add_f32_e32 v19, v28, v28
	v_fmamk_f32 v11, v48, 0x80000000, v28
	v_cndmask_b32_e64 v13, 0, v13, s[10:11]
	v_mul_f32_e32 v15, v48, v48
	v_mul_f32_e32 v19, v19, v48
	v_cndmask_b32_e64 v11, 1.0, v11, s[10:11]
	v_fma_f32 v15, v28, v28, -v15
	v_mul_f32_e32 v20, v19, v13
	v_fma_f32 v20, v15, v11, -v20
	v_mul_f32_e32 v21, v19, v11
	v_cndmask_b32_e64 v11, v11, v20, s[4:5]
	v_mul_f32_e32 v20, v19, v19
	v_fmac_f32_e32 v21, v15, v13
	v_fma_f32 v20, v15, v15, -v20
	v_add_f32_e32 v15, v15, v15
	v_cndmask_b32_e64 v13, v13, v21, s[4:5]
	v_mul_f32_e32 v15, v19, v15
	v_mul_f32_e32 v19, v15, v13
	v_fma_f32 v19, v20, v11, -v19
	v_mul_f32_e32 v21, v20, v13
	v_fmac_f32_e32 v21, v15, v11
	v_cndmask_b32_e64 v11, v11, v19, s[6:7]
	v_mul_f32_e32 v19, v15, v15
	v_fma_f32 v19, v20, v20, -v19
	v_add_f32_e32 v20, v20, v20
	v_cndmask_b32_e64 v13, v13, v21, s[6:7]
	v_mul_f32_e32 v15, v15, v20
	v_mul_f32_e32 v20, v15, v13
	v_fma_f32 v20, v19, v11, -v20
	v_mul_f32_e32 v19, v19, v13
	v_fmac_f32_e32 v19, v15, v11
	v_cndmask_b32_e64 v13, v13, v19, s[8:9]
	v_cndmask_b32_e64 v11, v11, v20, s[8:9]
	v_mul_f32_e32 v15, v7, v13
	v_fma_f32 v15, v6, v11, -v15
	v_mul_f32_e32 v6, v6, v13
	v_fmac_f32_e32 v6, v7, v11
	v_fma_f32 v11, 0, v29, v49
	v_add_f32_e32 v19, v29, v29
	v_fmamk_f32 v7, v49, 0x80000000, v29
	v_cndmask_b32_e64 v11, 0, v11, s[10:11]
	v_mul_f32_e32 v13, v49, v49
	v_mul_f32_e32 v19, v19, v49
	v_cndmask_b32_e64 v7, 1.0, v7, s[10:11]
	v_fma_f32 v13, v29, v29, -v13
	v_mul_f32_e32 v20, v19, v11
	v_fma_f32 v20, v13, v7, -v20
	v_mul_f32_e32 v21, v19, v7
	v_cndmask_b32_e64 v7, v7, v20, s[4:5]
	v_mul_f32_e32 v20, v19, v19
	v_fmac_f32_e32 v21, v13, v11
	v_fma_f32 v20, v13, v13, -v20
	v_add_f32_e32 v13, v13, v13
	v_cndmask_b32_e64 v11, v11, v21, s[4:5]
	v_mul_f32_e32 v13, v19, v13
	v_mul_f32_e32 v19, v13, v11
	v_fma_f32 v19, v20, v7, -v19
	v_mul_f32_e32 v21, v20, v11
	v_fmac_f32_e32 v21, v13, v7
	v_cndmask_b32_e64 v7, v7, v19, s[6:7]
	v_mul_f32_e32 v19, v13, v13
	v_fma_f32 v19, v20, v20, -v19
	v_add_f32_e32 v20, v20, v20
	v_cndmask_b32_e64 v11, v11, v21, s[6:7]
	v_mul_f32_e32 v13, v13, v20
	v_mul_f32_e32 v20, v13, v11
	v_fma_f32 v20, v19, v7, -v20
	v_mul_f32_e32 v19, v19, v11
	v_fmac_f32_e32 v19, v13, v7
	v_cndmask_b32_e64 v11, v11, v19, s[8:9]
	v_cndmask_b32_e64 v7, v7, v20, s[8:9]
	v_mul_f32_e32 v13, v9, v11
	v_fma_f32 v13, v8, v7, -v13
	v_mul_f32_e32 v8, v8, v11
	v_fmac_f32_e32 v8, v9, v7
	s_waitcnt vmcnt(0)
	v_fma_f32 v9, 0, v30, v22
	v_add_f32_e32 v19, v30, v30
	v_fmamk_f32 v7, v22, 0x80000000, v30
	v_cndmask_b32_e64 v9, 0, v9, s[10:11]
	v_mul_f32_e32 v11, v22, v22
	v_mul_f32_e32 v19, v19, v22
	v_cndmask_b32_e64 v7, 1.0, v7, s[10:11]
	v_fma_f32 v11, v30, v30, -v11
	v_mul_f32_e32 v20, v19, v9
	v_fma_f32 v20, v11, v7, -v20
	v_mul_f32_e32 v21, v19, v7
	v_cndmask_b32_e64 v7, v7, v20, s[4:5]
	v_mul_f32_e32 v20, v19, v19
	v_fmac_f32_e32 v21, v11, v9
	v_fma_f32 v20, v11, v11, -v20
	v_add_f32_e32 v11, v11, v11
	v_cndmask_b32_e64 v9, v9, v21, s[4:5]
	v_mul_f32_e32 v11, v19, v11
	v_mul_f32_e32 v19, v11, v9
	v_fma_f32 v19, v20, v7, -v19
	v_mul_f32_e32 v21, v20, v9
	v_fmac_f32_e32 v21, v11, v7
	v_cndmask_b32_e64 v7, v7, v19, s[6:7]
	v_mul_f32_e32 v19, v11, v11
	v_fma_f32 v19, v20, v20, -v19
	v_add_f32_e32 v20, v20, v20
	v_cndmask_b32_e64 v9, v9, v21, s[6:7]
	v_mul_f32_e32 v11, v11, v20
	v_mul_f32_e32 v20, v11, v9
	v_fma_f32 v20, v19, v7, -v20
	v_mul_f32_e32 v19, v19, v9
	v_fmac_f32_e32 v19, v11, v7
	v_cndmask_b32_e64 v9, v9, v19, s[8:9]
	v_cndmask_b32_e64 v7, v7, v20, s[8:9]
	v_mul_f32_e32 v11, v3, v9
	v_fma_f32 v11, v2, v7, -v11
	v_mul_f32_e32 v2, v2, v9
	v_fmac_f32_e32 v2, v3, v7
	v_fma_f32 v7, 0, v31, v23
	v_add_f32_e32 v19, v31, v31
	v_fmamk_f32 v3, v23, 0x80000000, v31
	v_cndmask_b32_e64 v7, 0, v7, s[10:11]
	v_mul_f32_e32 v9, v23, v23
	v_mul_f32_e32 v19, v19, v23
	v_cndmask_b32_e64 v3, 1.0, v3, s[10:11]
	v_fma_f32 v9, v31, v31, -v9
	v_mul_f32_e32 v20, v19, v7
	v_fma_f32 v20, v9, v3, -v20
	v_mul_f32_e32 v21, v19, v3
	v_cndmask_b32_e64 v3, v3, v20, s[4:5]
	v_mul_f32_e32 v20, v19, v19
	v_fmac_f32_e32 v21, v9, v7
	v_fma_f32 v20, v9, v9, -v20
	v_add_f32_e32 v9, v9, v9
	v_cndmask_b32_e64 v7, v7, v21, s[4:5]
	v_mul_f32_e32 v9, v19, v9
	v_mul_f32_e32 v19, v9, v7
	v_fma_f32 v19, v20, v3, -v19
	v_mul_f32_e32 v21, v20, v7
	v_fmac_f32_e32 v21, v9, v3
	v_cndmask_b32_e64 v3, v3, v19, s[6:7]
	v_mul_f32_e32 v19, v9, v9
	v_fma_f32 v19, v20, v20, -v19
	v_add_f32_e32 v20, v20, v20
	v_cndmask_b32_e64 v7, v7, v21, s[6:7]
	v_mul_f32_e32 v9, v9, v20
	v_mul_f32_e32 v20, v9, v7
	v_fma_f32 v20, v19, v3, -v20
	v_mul_f32_e32 v19, v19, v7
	v_fmac_f32_e32 v19, v9, v3
	v_and_b32_e32 v9, 64, v191
	v_add_u32_e32 v22, 64, v9
	v_xor_b32_e32 v9, 1, v191
	v_cmp_lt_i32_e32 vcc, v9, v22
	v_cndmask_b32_e64 v7, v7, v19, s[8:9]
	v_cndmask_b32_e64 v3, v3, v20, s[8:9]
	v_cndmask_b32_e32 v9, v191, v9, vcc
	v_lshlrev_b32_e32 v9, 2, v9
	v_mul_f32_e32 v20, v5, v7
	v_fma_f32 v20, v4, v3, -v20
	v_mul_f32_e32 v4, v4, v7
	ds_bpermute_b32 v7, v9, v36
	ds_bpermute_b32 v19, v9, v37
	ds_bpermute_b32 v21, v9, v38
	ds_bpermute_b32 v23, v9, v39
	v_fmac_f32_e32 v4, v5, v3
	s_waitcnt lgkmcnt(3)
	v_add_f32_e32 v7, v36, v7
	ds_bpermute_b32 v36, v9, v14
	s_waitcnt lgkmcnt(3)
	v_add_f32_e32 v3, v37, v19
	s_waitcnt lgkmcnt(2)
	v_add_f32_e32 v21, v38, v21
	s_waitcnt lgkmcnt(1)
	v_add_f32_e32 v23, v39, v23
	ds_bpermute_b32 v37, v9, v25
	ds_bpermute_b32 v38, v9, v16
	ds_bpermute_b32 v39, v9, v18
	ds_bpermute_b32 v24, v9, v40
	s_waitcnt lgkmcnt(4)
	v_add_f32_e32 v14, v14, v36
	ds_bpermute_b32 v36, v9, v10
	s_waitcnt lgkmcnt(4)
	v_add_f32_e32 v25, v25, v37
	s_waitcnt lgkmcnt(3)
	v_add_f32_e32 v16, v16, v38
	s_waitcnt lgkmcnt(2)
	v_add_f32_e32 v18, v18, v39
	ds_bpermute_b32 v37, v9, v17
	ds_bpermute_b32 v38, v9, v12
	ds_bpermute_b32 v39, v9, v15
	s_waitcnt lgkmcnt(4)
	v_add_f32_e32 v24, v40, v24
	ds_bpermute_b32 v40, v9, v6
	s_waitcnt lgkmcnt(4)
	v_add_f32_e32 v10, v10, v36
	ds_bpermute_b32 v36, v9, v13
	ds_bpermute_b32 v5, v9, v32
	ds_bpermute_b32 v19, v9, v33
	ds_bpermute_b32 v27, v9, v34
	ds_bpermute_b32 v30, v9, v35
	s_waitcnt lgkmcnt(8)
	v_add_f32_e32 v17, v17, v37
	s_waitcnt lgkmcnt(7)
	v_add_f32_e32 v12, v12, v38
	s_waitcnt lgkmcnt(6)
	v_add_f32_e32 v15, v15, v39
	ds_bpermute_b32 v37, v9, v8
	ds_bpermute_b32 v38, v9, v11
	ds_bpermute_b32 v39, v9, v2
	s_waitcnt lgkmcnt(8)
	v_add_f32_e32 v6, v6, v40
	ds_bpermute_b32 v40, v9, v20
	s_waitcnt lgkmcnt(8)
	v_add_f32_e32 v13, v13, v36
	v_xor_b32_e32 v36, 2, v191
	s_waitcnt lgkmcnt(7)
	v_add_f32_e32 v5, v32, v5
	s_waitcnt lgkmcnt(6)
	v_add_f32_e32 v19, v33, v19
	ds_bpermute_b32 v26, v9, v41
	ds_bpermute_b32 v28, v9, v42
	ds_bpermute_b32 v29, v9, v43
	s_waitcnt lgkmcnt(8)
	v_add_f32_e32 v27, v34, v27
	ds_bpermute_b32 v31, v9, v44
	ds_bpermute_b32 v32, v9, v45
	ds_bpermute_b32 v33, v9, v46
	ds_bpermute_b32 v34, v9, v47
	s_waitcnt lgkmcnt(11)
	v_add_f32_e32 v30, v35, v30
	ds_bpermute_b32 v35, v9, v50
	ds_bpermute_b32 v9, v9, v4
	v_cmp_lt_i32_e32 vcc, v36, v22
	s_waitcnt lgkmcnt(12)
	v_add_f32_e32 v8, v8, v37
	s_waitcnt lgkmcnt(11)
	v_add_f32_e32 v11, v11, v38
	v_cndmask_b32_e32 v36, v191, v36, vcc
	v_lshlrev_b32_e32 v36, 2, v36
	s_waitcnt lgkmcnt(10)
	v_add_f32_e32 v2, v2, v39
	ds_bpermute_b32 v37, v36, v3
	ds_bpermute_b32 v38, v36, v5
	ds_bpermute_b32 v39, v36, v7
	s_waitcnt lgkmcnt(12)
	v_add_f32_e32 v20, v20, v40
	ds_bpermute_b32 v40, v36, v19
	s_waitcnt lgkmcnt(4)
	v_add_f32_e32 v4, v4, v9
	ds_bpermute_b32 v9, v36, v21
	v_add_f32_e32 v26, v41, v26
	s_waitcnt lgkmcnt(4)
	v_add_f32_e32 v3, v3, v37
	s_waitcnt lgkmcnt(3)
	v_add_f32_e32 v5, v5, v38
	s_waitcnt lgkmcnt(2)
	v_add_f32_e32 v7, v7, v39
	ds_bpermute_b32 v37, v36, v23
	ds_bpermute_b32 v38, v36, v24
	ds_bpermute_b32 v39, v36, v26
	v_add_f32_e32 v28, v42, v28
	s_waitcnt lgkmcnt(4)
	v_add_f32_e32 v19, v19, v40
	ds_bpermute_b32 v40, v36, v27
	s_waitcnt lgkmcnt(4)
	v_add_f32_e32 v21, v21, v9
	ds_bpermute_b32 v9, v36, v28
	v_add_f32_e32 v29, v43, v29
	v_add_f32_e32 v31, v44, v31
	v_add_f32_e32 v32, v45, v32
	s_waitcnt lgkmcnt(4)
	v_add_f32_e32 v23, v23, v37
	s_waitcnt lgkmcnt(3)
	v_add_f32_e32 v24, v24, v38
	s_waitcnt lgkmcnt(2)
	v_add_f32_e32 v26, v26, v39
	ds_bpermute_b32 v37, v36, v29
	ds_bpermute_b32 v38, v36, v30
	ds_bpermute_b32 v39, v36, v31
	v_add_f32_e32 v33, v46, v33
	s_waitcnt lgkmcnt(4)
	v_add_f32_e32 v27, v27, v40
	ds_bpermute_b32 v40, v36, v32
	s_waitcnt lgkmcnt(4)
	v_add_f32_e32 v28, v28, v9
	ds_bpermute_b32 v9, v36, v33
	v_add_f32_e32 v34, v47, v34
	v_add_f32_e32 v35, v50, v35
	s_waitcnt lgkmcnt(4)
	v_add_f32_e32 v29, v29, v37
	s_waitcnt lgkmcnt(3)
	v_add_f32_e32 v30, v30, v38
	s_waitcnt lgkmcnt(2)
	v_add_f32_e32 v31, v31, v39
	ds_bpermute_b32 v37, v36, v34
	ds_bpermute_b32 v38, v36, v35
	ds_bpermute_b32 v39, v36, v14
	s_waitcnt lgkmcnt(4)
	v_add_f32_e32 v32, v32, v40
	ds_bpermute_b32 v40, v36, v25
	s_waitcnt lgkmcnt(4)
	v_add_f32_e32 v33, v33, v9
	ds_bpermute_b32 v9, v36, v16
	s_waitcnt lgkmcnt(4)
	v_add_f32_e32 v34, v34, v37
	s_waitcnt lgkmcnt(3)
	v_add_f32_e32 v35, v35, v38
	s_waitcnt lgkmcnt(2)
	v_add_f32_e32 v37, v14, v39
	ds_bpermute_b32 v14, v36, v18
	ds_bpermute_b32 v38, v36, v10
	s_waitcnt lgkmcnt(3)
	v_add_f32_e32 v25, v25, v40
	ds_bpermute_b32 v40, v36, v12
	s_waitcnt lgkmcnt(3)
	v_add_f32_e32 v41, v16, v9
	ds_bpermute_b32 v16, v36, v11
	s_waitcnt lgkmcnt(3)
	v_add_f32_e32 v42, v18, v14
	s_waitcnt lgkmcnt(2)
	v_add_f32_e32 v38, v10, v38
	ds_bpermute_b32 v9, v36, v15
	ds_bpermute_b32 v10, v36, v6
	ds_bpermute_b32 v14, v36, v8
	s_waitcnt lgkmcnt(4)
	v_add_f32_e32 v40, v12, v40
	ds_bpermute_b32 v12, v36, v13
	s_waitcnt lgkmcnt(4)
	v_add_f32_e32 v47, v11, v16
	v_xor_b32_e32 v11, 4, v191
	v_cmp_lt_i32_e32 vcc, v11, v22
	ds_bpermute_b32 v39, v36, v17
	s_waitcnt lgkmcnt(4)
	v_add_f32_e32 v43, v15, v9
	v_cndmask_b32_e32 v11, v191, v11, vcc
	s_waitcnt lgkmcnt(3)
	v_add_f32_e32 v6, v6, v10
	s_waitcnt lgkmcnt(2)
	v_add_f32_e32 v45, v8, v14
	ds_bpermute_b32 v8, v36, v2
	ds_bpermute_b32 v9, v36, v20
	ds_bpermute_b32 v10, v36, v4
	v_lshlrev_b32_e32 v36, 2, v11
	s_waitcnt lgkmcnt(4)
	v_add_f32_e32 v44, v13, v12
	ds_bpermute_b32 v11, v36, v3
	ds_bpermute_b32 v12, v36, v5
	s_waitcnt lgkmcnt(3)
	v_add_f32_e32 v48, v20, v9
	s_waitcnt lgkmcnt(2)
	v_add_f32_e32 v4, v4, v10
	v_add_f32_e32 v2, v2, v8
	s_waitcnt lgkmcnt(1)
	v_add_f32_e32 v9, v3, v11
	s_waitcnt lgkmcnt(0)
	v_add_f32_e32 v10, v5, v12
	ds_bpermute_b32 v3, v36, v7
	ds_bpermute_b32 v5, v36, v19
	ds_bpermute_b32 v12, v36, v23
	ds_bpermute_b32 v11, v36, v21
	ds_bpermute_b32 v13, v36, v24
	s_waitcnt lgkmcnt(4)
	v_add_f32_e32 v7, v7, v3
	s_waitcnt lgkmcnt(3)
	v_add_f32_e32 v8, v19, v5
	ds_bpermute_b32 v3, v36, v26
	ds_bpermute_b32 v5, v36, v27
	s_waitcnt lgkmcnt(4)
	v_add_f32_e32 v12, v23, v12
	ds_bpermute_b32 v14, v36, v28
	ds_bpermute_b32 v23, v36, v34
	s_waitcnt lgkmcnt(3)
	v_add_f32_e32 v16, v26, v3
	s_waitcnt lgkmcnt(2)
	v_add_f32_e32 v15, v27, v5
	ds_bpermute_b32 v3, v36, v31
	ds_bpermute_b32 v5, v36, v32
	v_add_f32_e32 v11, v21, v11
	v_add_f32_e32 v13, v24, v13
	ds_bpermute_b32 v18, v36, v30
	ds_bpermute_b32 v19, v36, v33
	ds_bpermute_b32 v24, v36, v35
	s_waitcnt lgkmcnt(4)
	v_add_f32_e32 v20, v31, v3
	s_waitcnt lgkmcnt(3)
	v_add_f32_e32 v21, v32, v5
	ds_bpermute_b32 v3, v36, v37
	ds_bpermute_b32 v5, v36, v25
	v_add_f32_e32 v14, v28, v14
	v_add_f32_e32 v28, v34, v23
	ds_bpermute_b32 v23, v36, v41
	v_add_f32_e32 v39, v17, v39
	s_waitcnt lgkmcnt(5)
	v_add_f32_e32 v18, v30, v18
	s_waitcnt lgkmcnt(4)
	v_add_f32_e32 v27, v33, v19
	s_waitcnt lgkmcnt(3)
	v_add_f32_e32 v19, v35, v24
	ds_bpermute_b32 v26, v36, v42
	s_waitcnt lgkmcnt(3)
	v_add_f32_e32 v24, v37, v3
	s_waitcnt lgkmcnt(2)
	v_add_f32_e32 v30, v25, v5
	ds_bpermute_b32 v3, v36, v39
	ds_bpermute_b32 v25, v36, v6
	ds_bpermute_b32 v17, v36, v29
	s_waitcnt lgkmcnt(4)
	v_add_f32_e32 v31, v41, v23
	ds_bpermute_b32 v5, v36, v40
	ds_bpermute_b32 v23, v36, v43
	s_waitcnt lgkmcnt(5)
	v_add_f32_e32 v33, v42, v26
	s_waitcnt lgkmcnt(4)
	v_add_f32_e32 v42, v39, v3
	s_waitcnt lgkmcnt(3)
	v_add_f32_e32 v39, v6, v25
	ds_bpermute_b32 v6, v36, v2
	s_waitcnt lgkmcnt(3)
	v_add_f32_e32 v17, v29, v17
	ds_bpermute_b32 v29, v36, v38
	ds_bpermute_b32 v26, v36, v44
	s_waitcnt lgkmcnt(4)
	v_add_f32_e32 v46, v40, v5
	s_waitcnt lgkmcnt(3)
	v_add_f32_e32 v40, v43, v23
	ds_bpermute_b32 v3, v36, v45
	ds_bpermute_b32 v5, v36, v47
	ds_bpermute_b32 v23, v36, v48
	ds_bpermute_b32 v25, v36, v4
	s_waitcnt lgkmcnt(6)
	v_add_f32_e32 v57, v2, v6
	v_xor_b32_e32 v2, 8, v191
	v_cmp_lt_i32_e32 vcc, v2, v22
	s_waitcnt lgkmcnt(5)
	v_add_f32_e32 v34, v38, v29
	s_waitcnt lgkmcnt(4)
	v_add_f32_e32 v49, v44, v26
	v_cndmask_b32_e32 v2, v191, v2, vcc
	s_waitcnt lgkmcnt(3)
	v_add_f32_e32 v52, v45, v3
	s_waitcnt lgkmcnt(2)
	v_add_f32_e32 v58, v47, v5
	s_waitcnt lgkmcnt(1)
	v_add_f32_e32 v62, v48, v23
	s_waitcnt lgkmcnt(0)
	v_add_f32_e32 v63, v4, v25
	v_lshlrev_b32_e32 v2, 2, v2
	ds_bpermute_b32 v25, v2, v9
	ds_bpermute_b32 v26, v2, v10
	ds_bpermute_b32 v22, v2, v7
	ds_bpermute_b32 v23, v2, v8
	ds_bpermute_b32 v29, v2, v11
	ds_bpermute_b32 v32, v2, v12
	ds_bpermute_b32 v37, v2, v13
	ds_bpermute_b32 v38, v2, v16
	ds_bpermute_b32 v36, v2, v15
	ds_bpermute_b32 v35, v2, v14
	ds_bpermute_b32 v44, v2, v17
	ds_bpermute_b32 v45, v2, v18
	ds_bpermute_b32 v47, v2, v20
	ds_bpermute_b32 v48, v2, v21
	ds_bpermute_b32 v53, v2, v27
	ds_bpermute_b32 v54, v2, v28
	ds_bpermute_b32 v43, v2, v19
	ds_bpermute_b32 v41, v2, v24
	ds_bpermute_b32 v50, v2, v30
	ds_bpermute_b32 v51, v2, v31
	ds_bpermute_b32 v55, v2, v33
	ds_bpermute_b32 v56, v2, v34
	ds_bpermute_b32 v61, v2, v42
	ds_bpermute_b32 v64, v2, v46
	ds_bpermute_b32 v60, v2, v40
	ds_bpermute_b32 v59, v2, v39
	ds_bpermute_b32 v66, v2, v49
	ds_bpermute_b32 v65, v2, v52
	ds_bpermute_b32 v68, v2, v58
	ds_bpermute_b32 v67, v2, v57
	ds_bpermute_b32 v69, v2, v62
	ds_bpermute_b32 v70, v2, v63
	v_lshlrev_b32_e32 v2, 4, v193
	v_and_b32_e32 v3, 0xfffffc00, v192
	v_or3_b32 v2, v2, v3, v87
	v_ashrrev_i32_e32 v3, 31, v2
	v_lshlrev_b64 v[2:3], 9, v[2:3]
	v_lshl_add_u64 v[2:3], s[38:39], 0, v[2:3]
	v_lshl_add_u64 v[2:3], v[2:3], 0, v[84:85]
	v_lshl_add_u64 v[2:3], v[2:3], 0, s[36:37]
	v_cmp_lt_i32_e32 vcc, 7, v82
	s_and_saveexec_b64 s[0:1], vcc
	s_xor_b64 s[0:1], exec, s[0:1]
	s_cbranch_execz .LBB0_412
	v_cmp_lt_i32_e32 vcc, 11, v82
	s_and_saveexec_b64 s[12:13], vcc
	s_xor_b64 s[12:13], exec, s[12:13]
	s_cbranch_execz .LBB0_397
	v_cmp_lt_i32_e32 vcc, 13, v82
	s_and_saveexec_b64 s[38:39], vcc
	s_xor_b64 s[38:39], exec, s[38:39]
	s_cbranch_execz .LBB0_390
	v_cmp_lt_i32_e32 vcc, 14, v82
	s_and_saveexec_b64 s[40:41], vcc
	s_xor_b64 s[40:41], exec, s[40:41]
	s_cbranch_execz .LBB0_387
	s_waitcnt lgkmcnt(1)
	v_add_f32_e32 v4, v62, v69
	s_waitcnt lgkmcnt(0)
	v_add_f32_e32 v6, v63, v70
	global_store_dword v[2:3], v4, off offset:228 sc0 sc1
.LBB0_387:
	s_or_saveexec_b64 s[40:41], s[40:41]
	v_mov_b64_e32 v[4:5], 0x1e4
	s_xor_b64 exec, exec, s[40:41]
	s_cbranch_execz .LBB0_389
	s_waitcnt lgkmcnt(3)
	v_add_f32_e32 v4, v58, v68
	s_waitcnt lgkmcnt(2)
	v_add_f32_e32 v6, v57, v67
	global_store_dword v[2:3], v4, off offset:224 sc0 sc1
	v_mov_b64_e32 v[4:5], 0x1e0

.LBB0_390:
	s_andn2_saveexec_b64 s[38:39], s[38:39]
	s_cbranch_execz .LBB0_396
	v_cmp_lt_i32_e32 vcc, 12, v82
	s_and_saveexec_b64 s[40:41], vcc
	s_xor_b64 s[40:41], exec, s[40:41]
	s_cbranch_execz .LBB0_393
	s_waitcnt lgkmcnt(5)
	v_add_f32_e32 v4, v49, v66
	s_waitcnt lgkmcnt(4)
	v_add_f32_e32 v6, v52, v65
	global_store_dword v[2:3], v4, off offset:196 sc0 sc1
.LBB0_393:
	s_or_saveexec_b64 s[40:41], s[40:41]
	v_mov_b64_e32 v[4:5], 0x1c4
	s_xor_b64 exec, exec, s[40:41]
	s_cbranch_execz .LBB0_395
	s_waitcnt lgkmcnt(7)
	v_add_f32_e32 v4, v40, v60
	s_waitcnt lgkmcnt(6)
	v_add_f32_e32 v6, v39, v59
	global_store_dword v[2:3], v4, off offset:192 sc0 sc1
	v_mov_b64_e32 v[4:5], 0x1c0

.LBB0_397:
	s_andn2_saveexec_b64 s[12:13], s[12:13]
	s_cbranch_execz .LBB0_411
	v_cmp_lt_i32_e32 vcc, 9, v82
	s_and_saveexec_b64 s[38:39], vcc
	s_xor_b64 s[38:39], exec, s[38:39]
	s_cbranch_execz .LBB0_404
	v_cmp_lt_i32_e32 vcc, 10, v82
	s_and_saveexec_b64 s[40:41], vcc
	s_xor_b64 s[40:41], exec, s[40:41]
	s_cbranch_execz .LBB0_401
	s_waitcnt lgkmcnt(9)
	v_add_f32_e32 v4, v42, v61
	s_waitcnt lgkmcnt(8)
	v_add_f32_e32 v6, v46, v64
	global_store_dword v[2:3], v4, off offset:164 sc0 sc1
.LBB0_401:
	s_or_saveexec_b64 s[40:41], s[40:41]
	v_mov_b64_e32 v[4:5], 0x1a4
	s_xor_b64 exec, exec, s[40:41]
	s_cbranch_execz .LBB0_403
	s_waitcnt lgkmcnt(11)
	v_add_f32_e32 v4, v33, v55
	s_waitcnt lgkmcnt(10)
	v_add_f32_e32 v6, v34, v56
	global_store_dword v[2:3], v4, off offset:160 sc0 sc1
	v_mov_b64_e32 v[4:5], 0x1a0

.LBB0_404:
	s_andn2_saveexec_b64 s[38:39], s[38:39]
	s_cbranch_execz .LBB0_410
	v_cmp_lt_i32_e32 vcc, 8, v82
	s_and_saveexec_b64 s[40:41], vcc
	s_xor_b64 s[40:41], exec, s[40:41]
	s_cbranch_execz .LBB0_407
	s_waitcnt lgkmcnt(13)
	v_add_f32_e32 v4, v30, v50
	s_waitcnt lgkmcnt(12)
	v_add_f32_e32 v6, v31, v51
	global_store_dword v[2:3], v4, off offset:132 sc0 sc1
.LBB0_407:
	s_or_saveexec_b64 s[40:41], s[40:41]
	v_mov_b64_e32 v[4:5], 0x184
	s_xor_b64 exec, exec, s[40:41]
	s_cbranch_execz .LBB0_409
	s_waitcnt lgkmcnt(14)
	v_add_f32_e32 v4, v19, v43
	v_add_f32_e32 v6, v24, v41
	global_store_dword v[2:3], v4, off offset:128 sc0 sc1
	v_mov_b64_e32 v[4:5], 0x180

.LBB0_412:
	s_andn2_saveexec_b64 s[0:1], s[0:1]
	s_cbranch_execz .LBB0_376
	v_cmp_lt_i32_e32 vcc, 3, v82
	s_and_saveexec_b64 s[12:13], vcc
	s_xor_b64 s[12:13], exec, s[12:13]
	s_cbranch_execz .LBB0_427
	v_cmp_lt_i32_e32 vcc, 5, v82
	s_and_saveexec_b64 s[38:39], vcc
	s_xor_b64 s[38:39], exec, s[38:39]
	s_cbranch_execz .LBB0_420
	v_cmp_lt_i32_e32 vcc, 6, v82
	s_and_saveexec_b64 s[40:41], vcc
	s_xor_b64 s[40:41], exec, s[40:41]
	s_cbranch_execz .LBB0_417
	s_waitcnt lgkmcnt(14)
	v_add_f32_e32 v4, v27, v53
	v_add_f32_e32 v6, v28, v54
	global_store_dword v[2:3], v4, off offset:100 sc0 sc1
.LBB0_417:
	s_or_saveexec_b64 s[40:41], s[40:41]
	v_mov_b64_e32 v[4:5], 0x164
	s_xor_b64 exec, exec, s[40:41]
	s_cbranch_execz .LBB0_419
	s_waitcnt lgkmcnt(14)
	v_add_f32_e32 v4, v20, v47
	v_add_f32_e32 v6, v21, v48
	global_store_dword v[2:3], v4, off offset:96 sc0 sc1
	v_mov_b64_e32 v[4:5], 0x160

.LBB0_420:
	s_andn2_saveexec_b64 s[38:39], s[38:39]
	s_cbranch_execz .LBB0_426
	v_cmp_lt_i32_e32 vcc, 4, v82
	s_and_saveexec_b64 s[40:41], vcc
	s_xor_b64 s[40:41], exec, s[40:41]
	s_cbranch_execz .LBB0_423
	s_waitcnt lgkmcnt(14)
	v_add_f32_e32 v4, v17, v44
	v_add_f32_e32 v6, v18, v45
	global_store_dword v[2:3], v4, off offset:68 sc0 sc1
.LBB0_423:
	s_or_saveexec_b64 s[40:41], s[40:41]
	v_mov_b64_e32 v[4:5], 0x144
	s_xor_b64 exec, exec, s[40:41]
	s_cbranch_execz .LBB0_425
	s_waitcnt lgkmcnt(14)
	v_add_f32_e32 v4, v15, v36
	v_add_f32_e32 v6, v14, v35
	global_store_dword v[2:3], v4, off offset:64 sc0 sc1
	v_mov_b64_e32 v[4:5], 0x140

.LBB0_427:
	s_andn2_saveexec_b64 s[12:13], s[12:13]
	s_cbranch_execz .LBB0_375
	v_cmp_lt_i32_e32 vcc, 1, v82
	s_and_saveexec_b64 s[38:39], vcc
	s_xor_b64 s[38:39], exec, s[38:39]
	s_cbranch_execz .LBB0_434
	v_cmp_lt_i32_e32 vcc, 2, v82
	s_and_saveexec_b64 s[40:41], vcc
	s_xor_b64 s[40:41], exec, s[40:41]
	s_cbranch_execz .LBB0_431
	s_waitcnt lgkmcnt(14)
	v_add_f32_e32 v4, v13, v37
	v_add_f32_e32 v6, v16, v38
	global_store_dword v[2:3], v4, off offset:36 sc0 sc1
.LBB0_431:
	s_or_saveexec_b64 s[40:41], s[40:41]
	v_mov_b64_e32 v[4:5], 0x124
	s_xor_b64 exec, exec, s[40:41]
	s_cbranch_execz .LBB0_433
	s_waitcnt lgkmcnt(14)
	v_add_f32_e32 v4, v11, v29
	v_add_f32_e32 v6, v12, v32
	global_store_dword v[2:3], v4, off offset:32 sc0 sc1
	v_mov_b64_e32 v[4:5], 0x120

.LBB0_434:
	s_andn2_saveexec_b64 s[38:39], s[38:39]
	s_cbranch_execz .LBB0_374
	v_cmp_ne_u32_e32 vcc, 1, v82
	s_and_saveexec_b64 s[40:41], vcc
	s_xor_b64 s[40:41], exec, s[40:41]
	s_cbranch_execz .LBB0_437
	s_waitcnt lgkmcnt(14)
	v_add_f32_e32 v6, v10, v26
	v_add_f32_e32 v4, v9, v25
	global_store_dword v[2:3], v4, off sc0 sc1
.LBB0_437:
	s_or_saveexec_b64 s[40:41], s[40:41]
	v_mov_b64_e32 v[4:5], 0x100
	s_xor_b64 exec, exec, s[40:41]
	s_cbranch_execz .LBB0_373
	s_waitcnt lgkmcnt(14)
	v_add_f32_e32 v4, v7, v22
	v_add_f32_e32 v6, v8, v23
	global_store_dword v[2:3], v4, off offset:4 sc0 sc1
	v_mov_b64_e32 v[4:5], 0x104
	s_branch .LBB0_373

.LBB0_460:
	s_andn2_saveexec_b64 s[4:5], s[4:5]
	s_cbranch_execz .LBB0_480
	s_mov_b64 s[4:5], exec
	s_waitcnt vmcnt(0)
	v_mbcnt_lo_u32_b32 v1, s4, 0
	v_mbcnt_hi_u32_b32 v1, s5, v1
	v_cmp_eq_u32_e32 vcc, 0, v1
	s_and_saveexec_b64 s[6:7], vcc
	s_cbranch_execz .LBB0_463
	s_bcnt1_i32_b64 s4, s[4:5]
	v_mov_b32_e32 v2, 0x3000
	v_mov_b32_e32 v3, s4
	global_atomic_add v2, v2, v3, s[88:89] offset:1024 sc0
